# FF1: drop half-filled row tile from the 256x256 unit order (exactly 8 rounds) and compute tail rows 32768.. with a direct-from-global MFMA routine over all WGs
# speedup vs baseline: 1.0120x; 1.0068x over previous
;     __device__ __forceinline__ bool next(int i, Unit& u) const { if (i != 0 || c >= n) return false; u.pm = pm; u.pn = c & 3; return true; }
;     __host__ __device__ bool next(int i, Unit& u) const {
;         const long L = (long)i * G + c; if (L >= nwg) return false;
;         int wgid = (int)L; { const int q = nwg / NXCD, r = nwg % NXCD, xcd = wgid % NXCD, off = wgid / NXCD; wgid = (xcd < r ? xcd * (q + 1) : r * (q + 1) + (xcd - r) * q) + off; }
; __global__ void __launch_bounds__(NT, 2) fwd_megakernel(Params p) {
;     ...
;     run_gemm(smem, XN, 1024, (const bf16_t*)(ws + OFF_FF1) + (size_t)layer * 4096 * 1024, 4096, 1024, pg8::EpiZ<1>{Z, 4096, 1 << 30, nullptr});
.LBB0_1009:
	s_or_b64 exec, exec, s[0:1]
	v_readlane_b32 s4, v253, 2
	v_readlane_b32 s6, v253, 4
	v_readlane_b32 s7, v253, 5
	s_add_u32 s14, s6, 0x3690000
	s_mul_i32 s0, s53, s52
	s_addc_u32 s15, s7, 0
	v_readlane_b32 s1, v253, 0
	s_mul_i32 s58, s0, s1
	s_add_u32 s0, s6, 0x3812300
	s_addc_u32 s1, s7, 0
	v_writelane_b32 v254, s0, 27
	v_readlane_b32 s5, v253, 3
	v_mbcnt_hi_u32_b32 v183, -1, v160
	v_writelane_b32 v254, s1, 28
	s_add_u32 s0, s6, 0x3812500
	s_addc_u32 s1, s7, 0
	v_writelane_b32 v253, s0, 24
	s_mov_b32 s62, 0x3d000000
	s_waitcnt lgkmcnt(0)
	v_and_b32_e32 v0, 64, v183
	v_writelane_b32 v253, s1, 25
	s_add_u32 s0, s6, 0x3812600
	s_addc_u32 s1, s7, 0
	s_add_u32 s72, s6, 0x3812700
	s_addc_u32 s73, s7, 0
	s_add_u32 s74, s6, 0x3812800
	v_writelane_b32 v253, s0, 26
	s_addc_u32 s75, s7, 0
	v_mov_b32_e32 v130, 0
	v_writelane_b32 v253, s1, 27
	s_add_u32 s0, s6, 0x3812900
	s_addc_u32 s1, s7, 0
	v_writelane_b32 v254, s0, 10
	v_mov_b32_e32 v132, 0x358637bd
	v_mov_b32_e32 v129, 0x22000
	v_writelane_b32 v254, s1, 11
	s_add_u32 s0, s6, 0x3812a00
	s_addc_u32 s1, s7, 0
	v_writelane_b32 v254, s0, 12
	v_mov_b32_e32 v133, 0x22004
	v_mov_b32_e32 v252, 0x1000
	v_writelane_b32 v254, s1, 13
	s_add_u32 s0, s6, 0x3812b00
	s_addc_u32 s1, s7, 0
	v_writelane_b32 v254, s0, 14
	v_mov_b32_e32 v180, 0x2000
	v_mov_b32_e32 v181, 1
	v_writelane_b32 v254, s1, 15
	s_add_u32 s0, s6, 0x3812c00
	s_addc_u32 s1, s7, 0
	v_writelane_b32 v254, s0, 16
	s_mov_b32 s63, 0x3c800000
	v_mov_b32_e32 v182, 0x22010
	v_writelane_b32 v254, s1, 17
	s_add_u32 s0, s6, 0x3812d00
	s_addc_u32 s1, s7, 0
	v_writelane_b32 v253, s0, 0
	v_add_u32_e32 v184, 64, v0
	v_xor_b32_e32 v185, 32, v183
	v_writelane_b32 v253, s1, 1
	s_add_u32 s0, s6, 0x3812e00
	s_addc_u32 s1, s7, 0
	v_writelane_b32 v254, s0, 29
	v_readlane_b32 s16, v253, 28
	v_readlane_b32 s17, v253, 29
	v_writelane_b32 v254, s1, 30
	s_add_u32 s0, s6, 0x3812f00
	s_addc_u32 s1, s7, 0
	v_writelane_b32 v254, s0, 31
	v_readlane_b32 s18, v253, 30
	v_readlane_b32 s19, v253, 31
	v_writelane_b32 v254, s1, 32
	s_add_u32 s0, s6, 0x3813000
	s_addc_u32 s1, s7, 0
	v_writelane_b32 v254, s0, 33
	v_readlane_b32 s20, v253, 32
	v_readlane_b32 s21, v253, 33
	v_writelane_b32 v254, s1, 34
	s_add_u32 s0, s6, 0x3813100
	s_addc_u32 s1, s7, 0
	s_add_u32 s84, s6, 0x3813200
	s_addc_u32 s85, s7, 0
	s_add_u32 s86, s6, 0x3813300
	s_addc_u32 s87, s7, 0
	s_add_u32 s90, s6, 0x3813400
	v_writelane_b32 v254, s0, 35
	s_addc_u32 s91, s7, 0
	v_readlane_b32 s22, v253, 34
	v_writelane_b32 v254, s1, 36
	s_add_u32 s0, s6, 0x3815500
	s_addc_u32 s1, s7, 0
	v_writelane_b32 v254, s0, 37
	v_readlane_b32 s23, v253, 35
	v_readlane_b32 s24, v253, 36
	v_writelane_b32 v254, s1, 38
	s_add_u32 s0, s6, 0x3815600
	s_addc_u32 s1, s7, 0
	s_ashr_i32 s33, s52, 31
	s_add_u32 s96, s6, 0x17c99900
	v_writelane_b32 v254, s0, 39
	s_addc_u32 s97, s7, 0
	v_readlane_b32 s26, v253, 38
	v_writelane_b32 v254, s1, 40
	s_add_u32 s0, s6, 0x17a95900
	s_addc_u32 s1, s7, 0
	s_add_u32 s88, s6, 0x109b5900
	v_writelane_b32 v254, s0, 41
	s_addc_u32 s89, s7, 0
	v_readlane_b32 s28, v253, 40
	v_writelane_b32 v254, s1, 42
	s_add_u32 s0, s6, 0x7895c00
	v_writelane_b32 v254, s0, 43
	s_addc_u32 s0, s7, 0
	s_add_u32 s12, s6, 0x13a15900
	s_addc_u32 s13, s7, 0
	v_writelane_b32 v254, s0, 44
	s_add_u32 s0, s6, 0x180a1900
	v_writelane_b32 v254, s0, 45
	s_addc_u32 s0, s7, 0
	s_lshl_b32 s57, s52, 9
	v_writelane_b32 v254, s0, 46
	s_add_u32 s0, s6, 0x3812000
	s_addc_u32 s1, s7, 0
	v_writelane_b32 v254, s0, 47
	v_readlane_b32 s29, v253, 41
	v_readlane_b32 s30, v253, 42
	v_writelane_b32 v254, s1, 48
	s_add_u32 s0, s6, 0x7895e40
	v_writelane_b32 v254, s0, 49
	s_addc_u32 s0, s7, 0
	v_writelane_b32 v254, s0, 50
	s_add_u32 s0, s6, 0x7896240
	v_writelane_b32 v254, s0, 51
	s_addc_u32 s0, s7, 0
	v_writelane_b32 v254, s0, 52
	s_add_u32 s0, s6, 0x7896640
	v_writelane_b32 v254, s0, 53
	s_addc_u32 s0, s7, 0
	v_writelane_b32 v254, s0, 54
	s_add_u32 s0, s6, 0x3815d00
	v_writelane_b32 v254, s0, 55
	s_addc_u32 s0, s7, 0
	v_writelane_b32 v254, s0, 56
	s_mov_b64 s[0:1], s[16:17]
	s_add_u32 s0, s0, 0x7000000
	s_addc_u32 s1, s1, 0
	v_writelane_b32 v254, s0, 57
	s_mov_b64 s[2:3], s[18:19]
	v_readlane_b32 s31, v253, 43
	v_writelane_b32 v254, s1, 58
	v_xor_b32_e32 v186, 16, v183
	v_readlane_b32 s0, v254, 20
	s_mul_hi_i32 s3, s0, 0x1200
	s_mul_i32 s2, s0, 0x1200
	v_readlane_b32 s1, v254, 21
	v_writelane_b32 v254, s2, 59
	s_ashr_i32 s1, s0, 31
	s_mov_b32 s80, s0
	v_writelane_b32 v254, s3, 60
	s_mov_b32 s2, 0
	v_writelane_b32 v254, s2, 61
	s_lshl_b64 s[2:3], s[0:1], 6
	v_writelane_b32 v254, s2, 62
	v_xor_b32_e32 v187, 8, v183
	v_xor_b32_e32 v191, 4, v183
	v_writelane_b32 v254, s3, 63
	s_lshl_b64 s[2:3], s[0:1], 7
	v_writelane_b32 v255, s2, 0
	s_lshl_b64 s[0:1], s[0:1], 5
	v_writelane_b32 v254, s96, 20
	v_writelane_b32 v255, s3, 1
	v_writelane_b32 v255, s0, 2
	v_xor_b32_e32 v192, 2, v183
	v_xor_b32_e32 v190, 1, v183
	v_writelane_b32 v255, s1, 3
	s_mov_b32 s1, 0
	v_writelane_b32 v255, s0, 4
	v_mov_b64_e32 v[134:135], 0x183
	v_mov_b64_e32 v[136:137], 0x182
	v_writelane_b32 v255, s1, 5
	s_mov_b64 s[0:1], -1
	v_writelane_b32 v255, s0, 6
	v_mov_b64_e32 v[138:139], 0x204
	v_mov_b64_e32 v[140:141], 0x203
	v_writelane_b32 v255, s1, 7
	v_writelane_b32 v255, s72, 8
	v_mov_b32_e32 v193, 0xf149f2ca
	v_mov_b64_e32 v[142:143], 0x200
	v_writelane_b32 v255, s73, 9
	v_writelane_b32 v255, s74, 10
	v_mov_b64_e32 v[144:145], 0x1ff
	v_mov_b64_e32 v[146:147], 0x800
	v_writelane_b32 v255, s75, 11
	v_writelane_b32 v255, s57, 12
	v_mov_b64_e32 v[148:149], 0x7ff
	s_movk_i32 s53, 0x1200
	s_mov_b32 s22, 0x8080
	s_mov_b32 s23, 0x7f807f81
	s_movk_i32 s24, 0xeff0
	s_movk_i32 s81, 0x7fff
	s_mov_b32 s82, 0x800000
	s_mov_b32 s26, 0x40000008
	s_mov_b32 s28, 0x3fffff88
	s_movk_i32 s29, 0x1010
	s_mov_b32 s30, 0xf149f2ca
	s_mov_b32 s31, 0xff61b1e6
	s_mov_b32 s34, 0x3e16c740
	s_movk_i32 s83, 0x7fe0
	s_mov_b64 s[0:1], 0
	s_mov_b64 s[54:55], 0x80
	v_writelane_b32 v254, s97, 21
	v_writelane_b32 v255, s58, 13
	s_barrier
	v_readlane_b32 s25, v253, 37
	v_readlane_b32 s27, v253, 39
	s_mov_b64 s[4:5], s[20:21]
	s_branch .LBB0_1012

;     __device__ __forceinline__ bool next(int i, Unit& u) const { if (i != 0 || c >= n) return false; u.pm = pm; u.pn = c & 3; return true; }
;     __host__ __device__ bool next(int i, Unit& u) const {
;         const long L = (long)i * G + c; if (L >= nwg) return false;
;         int wgid = (int)L; { const int q = nwg / NXCD, r = nwg % NXCD, xcd = wgid % NXCD, off = wgid / NXCD; wgid = (xcd < r ? xcd * (q + 1) : r * (q + 1) + (xcd - r) * q) + off; }
;         const int nig = WGM * nN, gid = wgid / nig, fm = gid * WGM, gsz = (nM - fm) < WGM ? (nM - fm) : WGM;
;         u.pm = fm + ((wgid % nig) % gsz); u.pn = (wgid % nig) / gsz; return true;
.LBB0_2166:
	s_mov_b32 s82, 0x800000
	s_or_b64 exec, exec, s[0:1]
	v_readlane_b32 s35, v254, 22
	s_waitcnt lgkmcnt(0)
	s_barrier
	v_mov_b32_e32 v0, v128
	s_cmpk_lt_i32 s35, 0x800
	s_movk_i32 s81, 0x7fff
	s_cselect_b64 s[2:3], -1, 0
	s_cmpk_gt_i32 s35, 0x7ff
	v_readfirstlane_b32 s10, v0
	s_cbranch_scc1 .LBB0_2168
	s_ashr_i32 s0, s35, 31
	s_lshr_b32 s0, s0, 29
	s_add_i32 s0, s35, s0
	s_ashr_i32 s1, s0, 3
	s_and_b32 s0, s0, -8
	s_sub_i32 s0, s35, s0
	s_cmp_lt_i32 s0, 0
	s_movk_i32 s4, 0x101
	s_cselect_b32 s4, s4, 0x100
	s_mul_i32 s0, s4, s0
	s_add_i32 s0, s0, s1
	s_ashr_i32 s1, s0, 31
	s_lshr_b32 s1, s1, 25
	s_add_i32 s1, s0, s1
	s_ashr_i32 s4, s1, 7
	s_lshl_b32 s4, s4, 3
	s_sub_i32 s5, 0x80, s4
	s_min_u32 s5, s5, 8
	s_and_b32 s1, s1, 0xffffff80
	s_sub_i32 s8, s0, s1
	v_cvt_f32_ubyte0_e32 v2, s5
	v_cvt_f32_i32_e32 v1, s8
	v_rcp_iflag_f32_e32 v3, v2
	s_ashr_i32 s0, s8, 30
	s_or_b32 s9, s0, 1
	v_mul_f32_e32 v3, v1, v3
	v_trunc_f32_e32 v3, v3
	v_fma_f32 v1, -v3, v2, v1
	v_cvt_i32_f32_e32 v3, v3
	v_cmp_ge_f32_e64 s[0:1], |v1|, v2
	s_and_b64 s[0:1], s[0:1], exec
	s_cselect_b32 s0, s9, 0
	v_readfirstlane_b32 s1, v3
	s_add_i32 s1, s1, s0
	s_sext_i32_i8 s0, s1
	s_mul_i32 s1, s1, s5
	s_sub_i32 s1, s8, s1
	s_sext_i32_i8 s1, s1
	s_add_i32 s4, s4, s1

;     __device__ __forceinline__ bool next(int i, Unit& u) const { if (i != 0 || c >= n) return false; u.pm = pm; u.pn = c & 3; return true; }
;     __host__ __device__ bool next(int i, Unit& u) const {
;         const long L = (long)i * G + c; if (L >= nwg) return false;
;         int wgid = (int)L; { const int q = nwg / NXCD, r = nwg % NXCD, xcd = wgid % NXCD, off = wgid / NXCD; wgid = (xcd < r ? xcd * (q + 1) : r * (q + 1) + (xcd - r) * q) + off; }
;         const int nig = WGM * nN, gid = wgid / nig, fm = gid * WGM, gsz = (nM - fm) < WGM ? (nM - fm) : WGM;
;         u.pm = fm + ((wgid % nig) % gsz); u.pn = (wgid % nig) / gsz; return true;
.LBB0_2174:
	s_add_i32 s74, s74, 1
	s_mul_i32 s1, s74, s33
	s_mul_hi_u32 s2, s74, s52
	s_add_i32 s2, s2, s1
	s_mul_i32 s1, s74, s52
	s_add_u32 s16, s1, s35
	s_addc_u32 s17, s2, s73
	v_cmp_gt_i64_e32 vcc, s[16:17], v[148:149]
	v_cmp_lt_i64_e64 s[2:3], s[16:17], v[146:147]
	s_cbranch_vccnz .LBB0_2176
	s_ashr_i32 s1, s16, 31
	s_lshr_b32 s1, s1, 29
	s_add_i32 s1, s16, s1
	s_ashr_i32 s5, s1, 3
	s_and_b32 s1, s1, -8
	s_sub_i32 s1, s16, s1
	s_cmp_lt_i32 s1, 0
	s_movk_i32 s16, 0x101
	s_cselect_b32 s16, s16, 0x100
	s_mul_i32 s1, s16, s1
	s_add_i32 s1, s1, s5
	s_ashr_i32 s5, s1, 31
	s_lshr_b32 s5, s5, 25
	s_add_i32 s5, s1, s5
	s_ashr_i32 s16, s5, 7
	s_lshl_b32 s16, s16, 3
	s_sub_i32 s17, 0x80, s16
	s_min_i32 s17, s17, 8
	s_abs_i32 s20, s17
	v_cvt_f32_u32_e32 v0, s20
	s_sub_i32 s25, 0, s20
	s_and_b32 s5, s5, 0xffffff80
	s_sub_i32 s1, s1, s5
	v_rcp_iflag_f32_e32 v0, v0
	s_abs_i32 s5, s1
	s_xor_b32 s21, s1, s17
	s_ashr_i32 s21, s21, 31
	v_mul_f32_e32 v0, 0x4f7ffffe, v0
	v_cvt_u32_f32_e32 v0, v0
	s_nop 0
	v_readfirstlane_b32 s27, v0
	s_mul_i32 s25, s25, s27
	s_mul_hi_u32 s25, s27, s25
	s_add_i32 s27, s27, s25
	s_mul_hi_u32 s25, s5, s27
	s_mul_i32 s27, s25, s20
	s_sub_i32 s5, s5, s27
	s_add_i32 s56, s25, 1
	s_sub_i32 s27, s5, s20
	s_cmp_ge_u32 s5, s20
	s_cselect_b32 s25, s56, s25
	s_cselect_b32 s5, s27, s5
	s_add_i32 s27, s25, 1
	s_cmp_ge_u32 s5, s20
	s_cselect_b32 s5, s27, s25
	s_xor_b32 s5, s5, s21
	s_sub_i32 s92, s5, s21
	s_mul_i32 s5, s92, s17
	s_sub_i32 s1, s1, s5
	s_add_i32 s96, s1, s16

; DEVI unsigned pk_bf16(float lo, float hi) { unsigned r; asm("v_cvt_pk_bf16_f32 %0, %1, %2" : "=v"(r) : "v"(lo), "v"(hi)); return r; }
;     __device__ __forceinline__ void operator()(const f32x4 (&acc)[2][2][4][2], const Unit& u, int wr, int wc, int fr, int fq) const {
;     ...
;                     if (ACT == 1) {
; #pragma unroll
;                         for (int j = 0; j < 4; ++j) { const float a = fmaxf(v0[j], 0.f), b = fmaxf(v1[j], 0.f); v0[j] = a * a; v1[j] = b * b; } }
;                     if (col < gate0) { u32x4 w; w.x = pk_bf16(v0[0], v0[1]); w.y = pk_bf16(v0[2], v0[3]); w.z = pk_bf16(v1[0], v1[1]); w.w = pk_bf16(v1[2], v1[3]); *(u32x4*)(O + (size_t)row * ldo + col) = w; }
; __global__ void __launch_bounds__(NT, 2) fwd_megakernel(Params p) {
;     ...
;     run_gemm(smem, XN, 1024, (const bf16_t*)(ws + OFF_FF1) + (size_t)layer * 4096 * 1024, 4096, 1024, pg8::EpiZ<1>{Z, 4096, 1 << 30, nullptr});
.LBB0_2280:
	v_readlane_b32 s8, v254, 18
	v_readlane_b32 s9, v254, 19
	v_readlane_b32 s10, v253, 60
	v_readlane_b32 s11, v253, 61
	v_readlane_b32 s0, v254, 22
	s_lshl_b32 s1, s62, 1
	s_add_u32 s10, s10, s1
	s_addc_u32 s11, s11, 0
	s_cmp_gt_u32 s0, 0xff
	s_cbranch_scc1 .Lff1t_done
	v_lshrrev_b32_e32 v210, 6, v128
	v_and_b32_e32 v211, 15, v128
	v_bfe_u32 v212, v128, 4, 2
	v_and_b32_e32 v213, 3, v210
	v_lshrrev_b32_e32 v214, 2, v210
	v_lshl_or_b32 v213, v213, 4, v211
	v_lshl_or_b32 v214, v214, 4, v211
	v_lshlrev_b32_e32 v217, 4, v212
	v_lshrrev_b32_e32 v218, 2, v210
	v_lshlrev_b32_e32 v218, 4, v218
	v_lshl_or_b32 v218, v212, 2, v218
.Lff1t_loop:
	s_and_b32 s1, s0, 1
	s_lshr_b32 s2, s0, 1
	s_lshl_b32 s1, s1, 6
	s_add_i32 s1, s1, 0x8000
	s_lshl_b32 s2, s2, 5
	v_add_u32_e32 v215, s1, v213
	v_add_u32_e32 v216, s2, v214
	v_lshl_add_u32 v204, v215, 11, v217
	v_mov_b32_e32 v205, 0
	v_lshl_add_u32 v206, v216, 11, v217
	v_mov_b32_e32 v207, 0
	v_lshl_add_u64 v[204:205], s[8:9], 0, v[204:205]
	v_lshl_add_u64 v[206:207], s[10:11], 0, v[206:207]
	v_add_u32_e32 v219, s2, v218
	v_lshlrev_b32_e32 v208, 13, v215
	v_lshl_add_u32 v208, v219, 1, v208
	v_mov_b32_e32 v209, 0
	v_lshl_add_u64 v[208:209], s[60:61], 0, v[208:209]
	global_load_dwordx4 v[0:3], v[204:205], off
	global_load_dwordx4 v[64:67], v[206:207], off
	global_load_dwordx4 v[4:7], v[204:205], off offset:64
	global_load_dwordx4 v[68:71], v[206:207], off offset:64
	global_load_dwordx4 v[8:11], v[204:205], off offset:128
	global_load_dwordx4 v[72:75], v[206:207], off offset:128
	global_load_dwordx4 v[12:15], v[204:205], off offset:192
	global_load_dwordx4 v[76:79], v[206:207], off offset:192
	global_load_dwordx4 v[16:19], v[204:205], off offset:256
	global_load_dwordx4 v[80:83], v[206:207], off offset:256
	global_load_dwordx4 v[20:23], v[204:205], off offset:320
	global_load_dwordx4 v[84:87], v[206:207], off offset:320
	global_load_dwordx4 v[24:27], v[204:205], off offset:384
	global_load_dwordx4 v[88:91], v[206:207], off offset:384
	global_load_dwordx4 v[28:31], v[204:205], off offset:448
	global_load_dwordx4 v[92:95], v[206:207], off offset:448
	global_load_dwordx4 v[32:35], v[204:205], off offset:512
	global_load_dwordx4 v[96:99], v[206:207], off offset:512
	global_load_dwordx4 v[36:39], v[204:205], off offset:576
	global_load_dwordx4 v[100:103], v[206:207], off offset:576
	global_load_dwordx4 v[40:43], v[204:205], off offset:640
	global_load_dwordx4 v[104:107], v[206:207], off offset:640
	global_load_dwordx4 v[44:47], v[204:205], off offset:704
	global_load_dwordx4 v[108:111], v[206:207], off offset:704
	global_load_dwordx4 v[48:51], v[204:205], off offset:768
	global_load_dwordx4 v[112:115], v[206:207], off offset:768
	global_load_dwordx4 v[52:55], v[204:205], off offset:832
	global_load_dwordx4 v[116:119], v[206:207], off offset:832
	global_load_dwordx4 v[56:59], v[204:205], off offset:896
	global_load_dwordx4 v[120:123], v[206:207], off offset:896
	global_load_dwordx4 v[60:63], v[204:205], off offset:960
	global_load_dwordx4 v[124:127], v[206:207], off offset:960
	s_waitcnt vmcnt(30)
	v_mfma_f32_16x16x32_bf16 v[200:203], v[64:67], v[0:3], 0
	global_load_dwordx4 v[0:3], v[204:205], off offset:1024
	global_load_dwordx4 v[64:67], v[206:207], off offset:1024
	s_waitcnt vmcnt(30)
	v_mfma_f32_16x16x32_bf16 v[200:203], v[68:71], v[4:7], v[200:203]
	global_load_dwordx4 v[4:7], v[204:205], off offset:1088
	global_load_dwordx4 v[68:71], v[206:207], off offset:1088
	s_waitcnt vmcnt(30)
	v_mfma_f32_16x16x32_bf16 v[200:203], v[72:75], v[8:11], v[200:203]
	global_load_dwordx4 v[8:11], v[204:205], off offset:1152
	global_load_dwordx4 v[72:75], v[206:207], off offset:1152
	s_waitcnt vmcnt(30)
	v_mfma_f32_16x16x32_bf16 v[200:203], v[76:79], v[12:15], v[200:203]
	global_load_dwordx4 v[12:15], v[204:205], off offset:1216
	global_load_dwordx4 v[76:79], v[206:207], off offset:1216
	s_waitcnt vmcnt(30)
	v_mfma_f32_16x16x32_bf16 v[200:203], v[80:83], v[16:19], v[200:203]
	global_load_dwordx4 v[16:19], v[204:205], off offset:1280
	global_load_dwordx4 v[80:83], v[206:207], off offset:1280
	s_waitcnt vmcnt(30)
; DEVI unsigned pk_bf16(float lo, float hi) { unsigned r; asm("v_cvt_pk_bf16_f32 %0, %1, %2" : "=v"(r) : "v"(lo), "v"(hi)); return r; }
;     __device__ __forceinline__ void operator()(const f32x4 (&acc)[2][2][4][2], const Unit& u, int wr, int wc, int fr, int fq) const {
;     ...
;                     if (ACT == 1) {
; #pragma unroll
;                         for (int j = 0; j < 4; ++j) { const float a = fmaxf(v0[j], 0.f), b = fmaxf(v1[j], 0.f); v0[j] = a * a; v1[j] = b * b; } }
;                     if (col < gate0) { u32x4 w; w.x = pk_bf16(v0[0], v0[1]); w.y = pk_bf16(v0[2], v0[3]); w.z = pk_bf16(v1[0], v1[1]); w.w = pk_bf16(v1[2], v1[3]); *(u32x4*)(O + (size_t)row * ldo + col) = w; }
	v_mfma_f32_16x16x32_bf16 v[200:203], v[84:87], v[20:23], v[200:203]
	global_load_dwordx4 v[20:23], v[204:205], off offset:1344
	global_load_dwordx4 v[84:87], v[206:207], off offset:1344
	s_waitcnt vmcnt(30)
	v_mfma_f32_16x16x32_bf16 v[200:203], v[88:91], v[24:27], v[200:203]
	global_load_dwordx4 v[24:27], v[204:205], off offset:1408
	global_load_dwordx4 v[88:91], v[206:207], off offset:1408
	s_waitcnt vmcnt(30)
	v_mfma_f32_16x16x32_bf16 v[200:203], v[92:95], v[28:31], v[200:203]
	global_load_dwordx4 v[28:31], v[204:205], off offset:1472
	global_load_dwordx4 v[92:95], v[206:207], off offset:1472
	s_waitcnt vmcnt(30)
	v_mfma_f32_16x16x32_bf16 v[200:203], v[96:99], v[32:35], v[200:203]
	global_load_dwordx4 v[32:35], v[204:205], off offset:1536
	global_load_dwordx4 v[96:99], v[206:207], off offset:1536
	s_waitcnt vmcnt(30)
	v_mfma_f32_16x16x32_bf16 v[200:203], v[100:103], v[36:39], v[200:203]
	global_load_dwordx4 v[36:39], v[204:205], off offset:1600
	global_load_dwordx4 v[100:103], v[206:207], off offset:1600
	s_waitcnt vmcnt(30)
	v_mfma_f32_16x16x32_bf16 v[200:203], v[104:107], v[40:43], v[200:203]
	global_load_dwordx4 v[40:43], v[204:205], off offset:1664
	global_load_dwordx4 v[104:107], v[206:207], off offset:1664
	s_waitcnt vmcnt(30)
	v_mfma_f32_16x16x32_bf16 v[200:203], v[108:111], v[44:47], v[200:203]
	global_load_dwordx4 v[44:47], v[204:205], off offset:1728
	global_load_dwordx4 v[108:111], v[206:207], off offset:1728
	s_waitcnt vmcnt(30)
	v_mfma_f32_16x16x32_bf16 v[200:203], v[112:115], v[48:51], v[200:203]
	global_load_dwordx4 v[48:51], v[204:205], off offset:1792
	global_load_dwordx4 v[112:115], v[206:207], off offset:1792
	s_waitcnt vmcnt(30)
	v_mfma_f32_16x16x32_bf16 v[200:203], v[116:119], v[52:55], v[200:203]
	global_load_dwordx4 v[52:55], v[204:205], off offset:1856
	global_load_dwordx4 v[116:119], v[206:207], off offset:1856
	s_waitcnt vmcnt(30)
	v_mfma_f32_16x16x32_bf16 v[200:203], v[120:123], v[56:59], v[200:203]
	global_load_dwordx4 v[56:59], v[204:205], off offset:1920
	global_load_dwordx4 v[120:123], v[206:207], off offset:1920
	s_waitcnt vmcnt(30)
	v_mfma_f32_16x16x32_bf16 v[200:203], v[124:127], v[60:63], v[200:203]
	global_load_dwordx4 v[60:63], v[204:205], off offset:1984
	global_load_dwordx4 v[124:127], v[206:207], off offset:1984
	s_waitcnt vmcnt(30)
	v_mfma_f32_16x16x32_bf16 v[200:203], v[64:67], v[0:3], v[200:203]
	s_waitcnt vmcnt(28)
	v_mfma_f32_16x16x32_bf16 v[200:203], v[68:71], v[4:7], v[200:203]
	s_waitcnt vmcnt(26)
	v_mfma_f32_16x16x32_bf16 v[200:203], v[72:75], v[8:11], v[200:203]
	s_waitcnt vmcnt(24)
	v_mfma_f32_16x16x32_bf16 v[200:203], v[76:79], v[12:15], v[200:203]
	s_waitcnt vmcnt(22)
	v_mfma_f32_16x16x32_bf16 v[200:203], v[80:83], v[16:19], v[200:203]
	s_waitcnt vmcnt(20)
	v_mfma_f32_16x16x32_bf16 v[200:203], v[84:87], v[20:23], v[200:203]
	s_waitcnt vmcnt(18)
	v_mfma_f32_16x16x32_bf16 v[200:203], v[88:91], v[24:27], v[200:203]
	s_waitcnt vmcnt(16)
	v_mfma_f32_16x16x32_bf16 v[200:203], v[92:95], v[28:31], v[200:203]
	s_waitcnt vmcnt(14)
	v_mfma_f32_16x16x32_bf16 v[200:203], v[96:99], v[32:35], v[200:203]
	s_waitcnt vmcnt(12)
	v_mfma_f32_16x16x32_bf16 v[200:203], v[100:103], v[36:39], v[200:203]
	s_waitcnt vmcnt(10)
	v_mfma_f32_16x16x32_bf16 v[200:203], v[104:107], v[40:43], v[200:203]
	s_waitcnt vmcnt(8)
	v_mfma_f32_16x16x32_bf16 v[200:203], v[108:111], v[44:47], v[200:203]
	s_waitcnt vmcnt(6)
	v_mfma_f32_16x16x32_bf16 v[200:203], v[112:115], v[48:51], v[200:203]
	s_waitcnt vmcnt(4)
	v_mfma_f32_16x16x32_bf16 v[200:203], v[116:119], v[52:55], v[200:203]
	s_waitcnt vmcnt(2)
	v_mfma_f32_16x16x32_bf16 v[200:203], v[120:123], v[56:59], v[200:203]
	s_waitcnt vmcnt(0)
	v_mfma_f32_16x16x32_bf16 v[200:203], v[124:127], v[60:63], v[200:203]
	s_nop 15
	s_nop 7
	v_max_f32_e32 v200, 0, v200
	v_max_f32_e32 v201, 0, v201
	v_max_f32_e32 v202, 0, v202
	v_max_f32_e32 v203, 0, v203
	v_mul_f32_e32 v200, v200, v200
	v_mul_f32_e32 v201, v201, v201
	v_mul_f32_e32 v202, v202, v202
	v_mul_f32_e32 v203, v203, v203
	v_cvt_pk_bf16_f32 v200, v200, v201
	v_cvt_pk_bf16_f32 v201, v202, v203
	global_store_dwordx2 v[208:209], v[200:201], off
	s_add_i32 s0, s0, s52
	s_cmp_lt_u32 s0, 0x100
	s_cbranch_scc1 .Lff1t_loop
